# P2 q-unit epilogue: both row-rstd values and the rope-table vectors requested up front (rope vectors once per 32-token half, copied into each rotary block) instead of a dependent load per block
# speedup vs baseline: 1.0412x; 1.0038x over previous
; #define G_LOAD(pr, qr, kt_) if (MODE != 1) { _Pragma("unroll") for (int r = 0; r < NP; ++r) pr[r] = *(const u32x4*)(pp + (size_t)(r * 128) * ldp + (kt_) * BK); \
;                               _Pragma("unroll") for (int r = 0; r < NQ; ++r) qr[r] = *(const u32x4*)(qp + (size_t)(r * 128) * ldq + (kt_) * BK); }
; #define G_STORE(pr, qr, so_) { unsigned char* w_ = wP + (so_); \
;                               _Pragma("unroll") for (int r = 0; r < NP; ++r) *(u32x4*)(w_ + r * 128 * LROW) = pr[r]; \
;                               _Pragma("unroll") for (int r = 0; r < NQ; ++r) *(u32x4*)(w_ + BI * LROW + r * 128 * LROW) = qr[r]; }
; #define F_LOAD(fa, fb, so_, ks_) { _Pragma("unroll") for (int it = 0; it < WI; ++it) fa[it] = *(const bf16x8*)(rP + (so_) + it * 32 * LROW + (ks_) * 32); \
;                                   _Pragma("unroll") for (int jt = 0; jt < 2; ++jt) fb[jt] = *(const bf16x8*)(rQ + (so_) + jt * 32 * LROW + (ks_) * 32); }
; #define G_MFMA(fa, fb) if (MODE != 2) { _Pragma("unroll") for (int it = 0; it < WI; ++it) _Pragma("unroll") for (int jt = 0; jt < 2; ++jt) \
;                             acc[it][jt] = __builtin_amdgcn_mfma_f32_32x32x16_bf16(fa[it], fb[jt], acc[it][jt], 0, 0, 0); }
; #define SB __builtin_amdgcn_sched_barrier(0);
; #define G_LOAD(pr, qr, kt_) if (MODE != 1) { _Pragma("unroll") for (int r = 0; r < NP; ++r) pr[r] = *(const u32x4*)(pp + (size_t)(r * 128) * ldp + (kt_) * BK); \
;                               _Pragma("unroll") for (int r = 0; r < NQ; ++r) qr[r] = *(const u32x4*)(qp + (size_t)(r * 128) * ldq + (kt_) * BK); }
;     ...
;     for (int kt = 0; kt < nk; kt += 2) {
;         const int k3 = min(kt + 3, nk - 1), k4 = min(kt + 4, nk - 1);
;         SB
;         G_LOAD(pb, qb, k3)
;         F_LOAD(fa1, fb1, cur, 1)
;         SB
;         G_MFMA(fa0, fb0)
;         SB
;         G_STORE(pa, qa, wr)
;         F_LOAD(fa0, fb0, nxt, 0)
;         SB
;         G_MFMA(fa1, fb1)
;         SB
;         __syncthreads();
;         { const int t_ = cur; cur = nxt; nxt = wr; wr = t_; }
;         SB
;         G_LOAD(pa, qa, k4)
;         F_LOAD(fa1, fb1, cur, 1)
;         SB
;         G_MFMA(fa0, fb0)
;         SB
;         G_STORE(pb, qb, wr)
;         F_LOAD(fa0, fb0, nxt, 0)
;         SB
;         G_MFMA(fa1, fb1)
;         SB
;         __syncthreads();
;         { const int t_ = cur; cur = nxt; nxt = wr; wr = t_; }
;     }
.LBB0_576:
	s_add_i32 s6, s6, 2
	s_mov_b32 s8, s7
	s_min_u32 s7, s6, 4
	s_lshl_b32 s14, s7, 6
	v_lshl_add_u64 v[178:179], v[172:173], 0, s[14:15]
	v_add_co_u32_e32 v196, vcc, s84, v178
	v_add_u32_e32 v177, s3, v171
	s_nop 0
	v_addc_co_u32_e32 v197, vcc, 0, v179, vcc
	global_load_dwordx4 v[192:195], v[178:179], off offset:192
	s_nop 0
	global_load_dwordx4 v[196:199], v[196:197], off offset:192
	v_lshl_add_u64 v[178:179], v[174:175], 0, s[14:15]
	v_add_co_u32_e32 v204, vcc, s84, v178
	s_nop 1
	v_addc_co_u32_e32 v205, vcc, 0, v179, vcc
	global_load_dwordx4 v[200:203], v[178:179], off offset:192
	s_nop 0
	global_load_dwordx4 v[204:207], v[204:205], off offset:192
	ds_read_b128 v[208:211], v177 offset:2080
	ds_read_b128 v[212:215], v177 offset:4640
	ds_read_b128 v[216:219], v177 offset:7200
	ds_read_b128 v[220:223], v177 offset:9760
	v_add_u32_e32 v177, s3, v176
	ds_read_b128 v[224:227], v177 offset:22560
	ds_read_b128 v[228:231], v177 offset:25120
	s_waitcnt lgkmcnt(9)
	v_mfma_f32_32x32x16_bf16 v[112:127], v[164:167], v[144:147], v[112:127]
	v_mfma_f32_32x32x16_bf16 v[48:63], v[164:167], v[148:151], v[48:63]
	s_waitcnt lgkmcnt(8)
	v_mfma_f32_32x32x16_bf16 v[96:111], v[160:163], v[144:147], v[96:111]
	v_mfma_f32_32x32x16_bf16 v[32:47], v[160:163], v[148:151], v[32:47]
	s_waitcnt lgkmcnt(7)
	v_mfma_f32_32x32x16_bf16 v[80:95], v[156:159], v[144:147], v[80:95]
	v_mfma_f32_32x32x16_bf16 v[16:31], v[156:159], v[148:151], v[16:31]
	s_waitcnt lgkmcnt(6)
	v_mfma_f32_32x32x16_bf16 v[64:79], v[152:155], v[144:147], v[64:79]
	v_mfma_f32_32x32x16_bf16 v[0:15], v[152:155], v[148:151], v[0:15]
	v_add_u32_e32 v144, s8, v168
	s_waitcnt vmcnt(7)
	ds_write_b128 v144, v[128:131] offset:2048
	s_waitcnt vmcnt(6)
	ds_write_b128 v144, v[132:135] offset:12288
	s_waitcnt vmcnt(5)
	ds_write_b128 v144, v[136:139] offset:22528
	s_waitcnt vmcnt(4)
	ds_write_b128 v144, v[140:143] offset:32768
	v_add_u32_e32 v177, s5, v171
	ds_read_b128 v[144:147], v177 offset:2048
	ds_read_b128 v[148:151], v177 offset:4608
	ds_read_b128 v[152:155], v177 offset:7168
	ds_read_b128 v[156:159], v177 offset:9728
	v_add_u32_e32 v178, s5, v176
	ds_read_b128 v[160:163], v178 offset:22528
	ds_read_b128 v[164:167], v178 offset:25088
	s_waitcnt lgkmcnt(11)
	v_mfma_f32_32x32x16_bf16 v[112:127], v[208:211], v[224:227], v[112:127]
	s_min_u32 s7, s6, 3
	s_waitcnt lgkmcnt(10)
	v_mfma_f32_32x32x16_bf16 v[48:63], v[208:211], v[228:231], v[48:63]
	v_mfma_f32_32x32x16_bf16 v[96:111], v[212:215], v[224:227], v[96:111]
	v_mfma_f32_32x32x16_bf16 v[32:47], v[212:215], v[228:231], v[32:47]
	v_mfma_f32_32x32x16_bf16 v[80:95], v[216:219], v[224:227], v[80:95]
	v_mfma_f32_32x32x16_bf16 v[16:31], v[216:219], v[228:231], v[16:31]
	v_mfma_f32_32x32x16_bf16 v[64:79], v[220:223], v[224:227], v[64:79]
	v_mfma_f32_32x32x16_bf16 v[0:15], v[220:223], v[228:231], v[0:15]
	s_waitcnt lgkmcnt(0)
	s_barrier
	s_lshl_b32 s14, s7, 6
	v_lshl_add_u64 v[128:129], v[172:173], 0, s[14:15]
	v_add_co_u32_e32 v132, vcc, s84, v128
	v_lshl_add_u64 v[136:137], v[174:175], 0, s[14:15]
	s_nop 0
	v_addc_co_u32_e32 v133, vcc, 0, v129, vcc
	v_add_co_u32_e32 v140, vcc, s84, v136
	global_load_dwordx4 v[128:131], v[128:129], off offset:256
	s_nop 0
	global_load_dwordx4 v[132:135], v[132:133], off offset:256
	v_addc_co_u32_e32 v141, vcc, 0, v137, vcc
	global_load_dwordx4 v[136:139], v[136:137], off offset:256
	s_nop 0
	global_load_dwordx4 v[140:143], v[140:141], off offset:256
	ds_read_b128 v[208:211], v177 offset:2080
	ds_read_b128 v[212:215], v177 offset:4640
	ds_read_b128 v[216:219], v177 offset:7200
	ds_read_b128 v[220:223], v177 offset:9760
	ds_read_b128 v[224:227], v178 offset:22560
	ds_read_b128 v[228:231], v178 offset:25120
	v_mfma_f32_32x32x16_bf16 v[112:127], v[144:147], v[160:163], v[112:127]
	v_mfma_f32_32x32x16_bf16 v[48:63], v[144:147], v[164:167], v[48:63]
	v_mfma_f32_32x32x16_bf16 v[96:111], v[148:151], v[160:163], v[96:111]
	v_mfma_f32_32x32x16_bf16 v[32:47], v[148:151], v[164:167], v[32:47]
	v_mfma_f32_32x32x16_bf16 v[80:95], v[152:155], v[160:163], v[80:95]
	v_mfma_f32_32x32x16_bf16 v[16:31], v[152:155], v[164:167], v[16:31]
	v_mfma_f32_32x32x16_bf16 v[64:79], v[156:159], v[160:163], v[64:79]
	v_mfma_f32_32x32x16_bf16 v[0:15], v[156:159], v[164:167], v[0:15]
	v_add_u32_e32 v144, s3, v168
	s_waitcnt vmcnt(7)
	ds_write_b128 v144, v[192:195] offset:2048
	s_waitcnt vmcnt(6)
	ds_write_b128 v144, v[196:199] offset:12288
	s_waitcnt vmcnt(5)
	ds_write_b128 v144, v[200:203] offset:22528
	s_waitcnt vmcnt(4)
	ds_write_b128 v144, v[204:207] offset:32768
	v_add_u32_e32 v144, s8, v171
	ds_read_b128 v[164:167], v144 offset:2048
	ds_read_b128 v[160:163], v144 offset:4608
	ds_read_b128 v[156:159], v144 offset:7168
	ds_read_b128 v[152:155], v144 offset:9728
	v_add_u32_e32 v148, s8, v176
	ds_read_b128 v[144:147], v148 offset:22528
	ds_read_b128 v[148:151], v148 offset:25088
	s_waitcnt lgkmcnt(11)
	v_mfma_f32_32x32x16_bf16 v[112:127], v[208:211], v[224:227], v[112:127]
	s_waitcnt lgkmcnt(10)
	v_mfma_f32_32x32x16_bf16 v[48:63], v[208:211], v[228:231], v[48:63]
	v_mfma_f32_32x32x16_bf16 v[96:111], v[212:215], v[224:227], v[96:111]
	v_mfma_f32_32x32x16_bf16 v[32:47], v[212:215], v[228:231], v[32:47]
	v_mfma_f32_32x32x16_bf16 v[80:95], v[216:219], v[224:227], v[80:95]
	v_mfma_f32_32x32x16_bf16 v[16:31], v[216:219], v[228:231], v[16:31]
	v_mfma_f32_32x32x16_bf16 v[64:79], v[220:223], v[224:227], v[64:79]
	v_mfma_f32_32x32x16_bf16 v[0:15], v[220:223], v[228:231], v[0:15]
	s_cmp_lt_u32 s6, 6
	s_mov_b32 s7, s5
	s_mov_b32 s5, s3
	s_mov_b32 s3, s8
	s_waitcnt lgkmcnt(0)
	s_barrier
	s_cbranch_scc1 .LBB0_576
; DI void phase2(const Params& p, unsigned char* smem, int tid) {
;     ...
;             for (int jt = 0; jt < 2; ++jt) {
;                 const int tl = wj * 64 + jt * 32 + ln, t = tt * 256 + tl;
;                 const float rq = MLA_QS / sqrtf(((const float*)(ws + OFF_SSQC))[t] * (1.0f / 256) + EPS);
;                 const int pos = t % L;
; #pragma unroll
;                 for (int it = 0; it < 4; ++it) {
;                     const int blk = (f * 256 + wi * 128 + it * 32) >> 5, hd = blk / 3, part = blk - hd * 3;
;                     if (part < 2) {
; #pragma unroll
;                         for (int r = 0; r < 16; ++r) acc[it][jt][r] *= rq;
;                     } else {
;                         const float* rp = rope + (size_t)pos * 32;
; #pragma unroll
;                         for (int g = 0; g < 2; ++g) {
;                             const f32x4 c4 = *(const f32x4*)(rp + 8 * g + 4 * h), s4 = *(const f32x4*)(rp + 16 + 8 * g + 4 * h);
; #pragma unroll
;                             for (int e = 0; e < 4; ++e) {
;                                 const float x1 = acc[it][jt][4 * g + e] * rq, x2 = acc[it][jt][4 * g + e + 8] * rq;
;                                 acc[it][jt][4 * g + e] = x1 * c4[e] - x2 * s4[e]; acc[it][jt][4 * g + e + 8] = x1 * s4[e] + x2 * c4[e];
;                             }
;                         }
;                     }
	v_mov_b32_e32 v150, v188
	s_lshl_b32 s3, s4, 8
	s_waitcnt vmcnt(3)
	v_and_b32_e32 v128, 0xdf, v150
	v_or_b32_e32 v144, s3, v128
	v_ashrrev_i32_e32 v145, 31, v144
	v_lshl_add_u64 v[128:129], v[144:145], 2, s[34:35]
	global_load_dword v130, v[128:129], off
	global_load_dword v254, v[128:129], off offset:128
	v_ashrrev_i32_e32 v128, 1, v150
	v_lshrrev_b32_e32 v129, 3, v150
	s_lshl_b32 s2, s2, 8
	v_and_b32_e32 v128, 0xffffff80, v128
	v_and_b32_e32 v129, 4, v129
	v_mul_hi_i32 v131, v144, s62
	v_add_u32_e32 v128, s2, v128
	v_lshlrev_b32_e32 v168, 2, v129
	v_lshrrev_b32_e32 v129, 31, v131
	v_ashrrev_i32_e32 v131, 11, v131
	v_ashrrev_i32_e32 v145, 5, v128
	v_add_u32_e32 v128, v131, v129
	v_mul_hi_i32 v129, v145, s87
	v_mul_i32_i24_e32 v128, 0x1010, v128
	v_lshrrev_b32_e32 v131, 31, v129
	v_sub_u32_e32 v128, v144, v128
	v_add_u32_e32 v131, v129, v131
	v_ashrrev_i32_e32 v129, 31, v128
	v_lshlrev_b64 v[128:129], 7, v[128:129]
	v_lshl_add_u64 v[128:129], s[18:19], 0, v[128:129]
	v_lshl_add_u64 v[148:149], v[128:129], 0, v[168:169]
	global_load_dwordx4 v[232:235], v[148:149], off
	global_load_dwordx4 v[236:239], v[148:149], off offset:32
	global_load_dwordx4 v[240:243], v[148:149], off offset:64
	global_load_dwordx4 v[248:251], v[148:149], off offset:96
	v_lshl_add_u32 v131, v131, 1, v131
	v_sub_u32_e32 v131, v145, v131
	s_waitcnt vmcnt(5)
	v_fmamk_f32 v130, v130, 0x3b800000, v181
	v_mul_f32_e32 v132, 0x4f800000, v130
	v_cmp_gt_f32_e32 vcc, s85, v130
	s_nop 1
	v_cndmask_b32_e32 v130, v130, v132, vcc
	v_sqrt_f32_e32 v132, v130
	s_nop 0
	v_add_u32_e32 v133, -1, v132
	v_add_u32_e32 v134, 1, v132
	v_fma_f32 v135, -v133, v132, v130
	v_fma_f32 v136, -v134, v132, v130
	v_cmp_ge_f32_e64 s[4:5], 0, v135
	s_nop 1
	v_cndmask_b32_e64 v132, v132, v133, s[4:5]
	v_cmp_lt_f32_e64 s[4:5], 0, v136
	s_nop 1
	v_cndmask_b32_e64 v132, v132, v134, s[4:5]
	v_mul_f32_e32 v133, 0x37800000, v132
	v_cndmask_b32_e32 v132, v132, v133, vcc
	v_cmp_class_f32_e32 vcc, v130, v182
	s_nop 1
	v_cndmask_b32_e32 v130, v132, v130, vcc
	v_div_scale_f32 v132, s[4:5], v130, v130, s86
	v_rcp_f32_e32 v133, v132
	v_div_scale_f32 v128, vcc, s86, v130, s86
	v_cmp_lt_i32_e64 s[4:5], 1, v131
	v_fma_f32 v129, -v132, v133, 1.0
	v_fmac_f32_e32 v133, v129, v133
	v_mul_f32_e32 v129, v128, v133
	v_fma_f32 v134, -v132, v129, v128
	v_fmac_f32_e32 v129, v134, v133
	v_fma_f32 v128, -v132, v129, v128
	v_div_fmas_f32 v128, v128, v133, v129
	v_div_fixup_f32 v146, v128, v130, s86
	s_and_saveexec_b64 s[6:7], s[4:5]
	s_xor_b64 s[6:7], exec, s[6:7]
	s_cbranch_execz .LBB0_579
	s_waitcnt vmcnt(0)
	v_mov_b64_e32 v[128:129], v[240:241]
	v_mov_b64_e32 v[130:131], v[242:243]
	s_waitcnt vmcnt(0)
	v_mov_b64_e32 v[132:133], v[248:249]
	v_mov_b64_e32 v[134:135], v[250:251]
	s_waitcnt vmcnt(0)
	v_mov_b64_e32 v[152:153], v[236:237]
	v_mov_b64_e32 v[154:155], v[238:239]
	s_waitcnt vmcnt(0)
	v_mov_b64_e32 v[136:137], v[232:233]
	v_mov_b64_e32 v[138:139], v[234:235]
	v_mov_b32_e32 v172, v127
	v_mov_b32_e32 v173, v119
	v_pk_mul_f32 v[172:173], v[172:173], v[146:147] op_sel_hi:[1,0]
	v_mul_f32_e32 v166, v118, v146
	v_mul_f32_e32 v142, v126, v146
	v_mov_b32_e32 v143, v172
	v_pk_mul_f32 v[140:141], v[112:113], v[146:147] op_sel_hi:[1,0]
	v_pk_mul_f32 v[156:157], v[120:121], v[146:147] op_sel_hi:[1,0]
	v_pk_mul_f32 v[158:159], v[114:115], v[146:147] op_sel_hi:[1,0]
	v_pk_mul_f32 v[160:161], v[122:123], v[146:147] op_sel_hi:[1,0]
	v_pk_mul_f32 v[162:163], v[116:117], v[146:147] op_sel_hi:[1,0]
	v_pk_mul_f32 v[164:165], v[124:125], v[146:147] op_sel_hi:[1,0]
	v_mov_b32_e32 v167, v173
	s_waitcnt vmcnt(0)
	v_pk_mul_f32 v[174:175], v[156:157], v[128:129]
	s_waitcnt vmcnt(0)
	v_mul_f32_e32 v194, v166, v134
	v_pk_mul_f32 v[198:199], v[142:143], v[134:135]
	s_waitcnt vmcnt(0)
	v_mov_b32_e32 v134, v155
	v_pk_mul_f32 v[134:135], v[172:173], v[134:135]
	v_pk_mul_f32 v[128:129], v[140:141], v[128:129]
	v_pk_mul_f32 v[176:177], v[160:161], v[130:131]
	v_pk_mul_f32 v[130:131], v[158:159], v[130:131]
	v_pk_mul_f32 v[178:179], v[164:165], v[132:133]
	v_pk_mul_f32 v[192:193], v[162:163], v[132:133]
	v_mul_f32_e32 v196, v142, v154
	v_mov_b32_e32 v197, v134
	v_mov_b32_e32 v195, v135
	s_waitcnt vmcnt(0)
	v_pk_fma_f32 v[142:143], v[140:141], v[136:137], v[174:175] neg_lo:[0,0,1] neg_hi:[0,0,1]
	v_pk_fma_f32 v[132:133], v[156:157], v[136:137], v[128:129]
	v_pk_fma_f32 v[140:141], v[158:159], v[138:139], v[176:177] neg_lo:[0,0,1] neg_hi:[0,0,1]
	v_pk_fma_f32 v[130:131], v[160:161], v[138:139], v[130:131]
	v_pk_fma_f32 v[138:139], v[162:163], v[152:153], v[178:179] neg_lo:[0,0,1] neg_hi:[0,0,1]
	v_pk_fma_f32 v[128:129], v[164:165], v[152:153], v[192:193]
	v_pk_fma_f32 v[136:137], v[166:167], v[154:155], v[198:199] neg_lo:[0,0,1] neg_hi:[0,0,1]
	v_pk_add_f32 v[134:135], v[196:197], v[194:195]
; DI void phase2(const Params& p, unsigned char* smem, int tid) {
;     ...
;                 for (int it = 0; it < 4; ++it) {
;                     const int blk = (f * 256 + wi * 128 + it * 32) >> 5, hd = blk / 3, part = blk - hd * 3;
;                     if (part < 2) {
; #pragma unroll
;                         for (int r = 0; r < 16; ++r) acc[it][jt][r] *= rq;
;                     } else {
;                         const float* rp = rope + (size_t)pos * 32;
; #pragma unroll
;                         for (int g = 0; g < 2; ++g) {
;                             const f32x4 c4 = *(const f32x4*)(rp + 8 * g + 4 * h), s4 = *(const f32x4*)(rp + 16 + 8 * g + 4 * h);
; #pragma unroll
;                             for (int e = 0; e < 4; ++e) {
;                                 const float x1 = acc[it][jt][4 * g + e] * rq, x2 = acc[it][jt][4 * g + e + 8] * rq;
;                                 acc[it][jt][4 * g + e] = x1 * c4[e] - x2 * s4[e]; acc[it][jt][4 * g + e + 8] = x1 * s4[e] + x2 * c4[e];
;                             }
;                         }
;                     }
.LBB0_579:
	s_andn2_saveexec_b64 s[6:7], s[6:7]
	v_pk_mul_f32 v[134:135], v[126:127], v[146:147] op_sel_hi:[1,0]
	v_pk_mul_f32 v[128:129], v[124:125], v[146:147] op_sel_hi:[1,0]
	v_pk_mul_f32 v[130:131], v[122:123], v[146:147] op_sel_hi:[1,0]
	v_pk_mul_f32 v[132:133], v[120:121], v[146:147] op_sel_hi:[1,0]
	v_pk_mul_f32 v[136:137], v[118:119], v[146:147] op_sel_hi:[1,0]
	v_pk_mul_f32 v[138:139], v[116:117], v[146:147] op_sel_hi:[1,0]
	v_pk_mul_f32 v[140:141], v[114:115], v[146:147] op_sel_hi:[1,0]
	v_pk_mul_f32 v[142:143], v[112:113], v[146:147] op_sel_hi:[1,0]
	s_or_b64 exec, exec, s[6:7]
	v_or_b32_e32 v112, 1, v145
	v_mul_hi_i32 v113, v112, s87
	v_lshrrev_b32_e32 v114, 31, v113
	v_add_u32_e32 v113, v113, v114
	v_lshl_add_u32 v113, v113, 1, v113
	v_sub_u32_e32 v112, v112, v113
	v_cmp_lt_i32_e64 s[6:7], 1, v112
	s_and_saveexec_b64 s[8:9], s[6:7]
	s_xor_b64 s[8:9], exec, s[8:9]
	s_cbranch_execz .LBB0_583
	s_waitcnt vmcnt(0)
	v_mov_b64_e32 v[112:113], v[240:241]
	v_mov_b64_e32 v[114:115], v[242:243]
	s_waitcnt vmcnt(0)
	v_mov_b64_e32 v[118:119], v[248:249]
	v_mov_b64_e32 v[120:121], v[250:251]
	s_waitcnt vmcnt(0)
	v_mov_b64_e32 v[152:153], v[236:237]
	v_mov_b64_e32 v[154:155], v[238:239]
	s_waitcnt vmcnt(0)
	v_mov_b64_e32 v[156:157], v[232:233]
	v_mov_b64_e32 v[158:159], v[234:235]
	v_mov_b32_e32 v172, v111
	v_mov_b32_e32 v173, v103
	v_pk_mul_f32 v[172:173], v[172:173], v[146:147] op_sel_hi:[1,0]
	v_mul_f32_e32 v166, v102, v146
	v_mul_f32_e32 v126, v110, v146
	v_mov_b32_e32 v127, v172
	v_pk_mul_f32 v[116:117], v[96:97], v[146:147] op_sel_hi:[1,0]
	v_pk_mul_f32 v[122:123], v[104:105], v[146:147] op_sel_hi:[1,0]
	v_pk_mul_f32 v[124:125], v[98:99], v[146:147] op_sel_hi:[1,0]
	v_pk_mul_f32 v[160:161], v[106:107], v[146:147] op_sel_hi:[1,0]
	v_pk_mul_f32 v[162:163], v[100:101], v[146:147] op_sel_hi:[1,0]
	v_pk_mul_f32 v[164:165], v[108:109], v[146:147] op_sel_hi:[1,0]
	v_mov_b32_e32 v167, v173
	s_waitcnt vmcnt(0)
	v_pk_mul_f32 v[174:175], v[122:123], v[112:113]
	s_waitcnt vmcnt(0)
	v_mul_f32_e32 v192, v166, v120
	v_pk_mul_f32 v[196:197], v[126:127], v[120:121]
	s_waitcnt vmcnt(0)
	v_mov_b32_e32 v120, v155
	v_pk_mul_f32 v[120:121], v[172:173], v[120:121]
	v_pk_mul_f32 v[112:113], v[116:117], v[112:113]
	v_pk_mul_f32 v[176:177], v[160:161], v[114:115]
	v_pk_mul_f32 v[114:115], v[124:125], v[114:115]
	v_pk_mul_f32 v[178:179], v[164:165], v[118:119]
	v_pk_mul_f32 v[118:119], v[162:163], v[118:119]
	v_mul_f32_e32 v194, v126, v154
	v_mov_b32_e32 v195, v120
	v_mov_b32_e32 v193, v121
	s_waitcnt vmcnt(0)
	v_pk_fma_f32 v[126:127], v[116:117], v[156:157], v[174:175] neg_lo:[0,0,1] neg_hi:[0,0,1]
	v_pk_fma_f32 v[116:117], v[122:123], v[156:157], v[112:113]
	v_pk_fma_f32 v[124:125], v[124:125], v[158:159], v[176:177] neg_lo:[0,0,1] neg_hi:[0,0,1]
	v_pk_fma_f32 v[114:115], v[160:161], v[158:159], v[114:115]
	v_pk_fma_f32 v[122:123], v[162:163], v[152:153], v[178:179] neg_lo:[0,0,1] neg_hi:[0,0,1]
	v_pk_fma_f32 v[112:113], v[164:165], v[152:153], v[118:119]
	v_pk_fma_f32 v[118:119], v[166:167], v[154:155], v[196:197] neg_lo:[0,0,1] neg_hi:[0,0,1]
	v_pk_add_f32 v[120:121], v[194:195], v[192:193]
.LBB0_583:
	s_andn2_saveexec_b64 s[8:9], s[8:9]
	v_pk_mul_f32 v[120:121], v[110:111], v[146:147] op_sel_hi:[1,0]
	v_pk_mul_f32 v[112:113], v[108:109], v[146:147] op_sel_hi:[1,0]
	v_pk_mul_f32 v[114:115], v[106:107], v[146:147] op_sel_hi:[1,0]
	v_pk_mul_f32 v[116:117], v[104:105], v[146:147] op_sel_hi:[1,0]
	v_pk_mul_f32 v[118:119], v[102:103], v[146:147] op_sel_hi:[1,0]
	v_pk_mul_f32 v[122:123], v[100:101], v[146:147] op_sel_hi:[1,0]
	v_pk_mul_f32 v[124:125], v[98:99], v[146:147] op_sel_hi:[1,0]
	v_pk_mul_f32 v[126:127], v[96:97], v[146:147] op_sel_hi:[1,0]
	s_or_b64 exec, exec, s[8:9]
	v_or_b32_e32 v96, 2, v145
	v_mul_hi_i32 v97, v96, s87
	v_lshrrev_b32_e32 v98, 31, v97
	v_add_u32_e32 v97, v97, v98
	v_lshl_add_u32 v97, v97, 1, v97
	v_sub_u32_e32 v96, v96, v97
	v_cmp_lt_i32_e64 s[8:9], 1, v96
	s_and_saveexec_b64 s[10:11], s[8:9]
	s_xor_b64 s[10:11], exec, s[10:11]
	s_cbranch_execz .LBB0_587
	s_waitcnt vmcnt(0)
	v_mov_b64_e32 v[96:97], v[240:241]
	v_mov_b64_e32 v[98:99], v[242:243]
	s_waitcnt vmcnt(0)
	v_mov_b64_e32 v[102:103], v[248:249]
	v_mov_b64_e32 v[104:105], v[250:251]
	s_waitcnt vmcnt(0)
	v_mov_b64_e32 v[152:153], v[236:237]
	v_mov_b64_e32 v[154:155], v[238:239]
	s_waitcnt vmcnt(0)
	v_mov_b64_e32 v[156:157], v[232:233]
	v_mov_b64_e32 v[158:159], v[234:235]
	v_mov_b32_e32 v172, v95
	v_mov_b32_e32 v173, v87
	v_pk_mul_f32 v[172:173], v[172:173], v[146:147] op_sel_hi:[1,0]
	v_mul_f32_e32 v166, v86, v146
	v_mul_f32_e32 v110, v94, v146
	v_mov_b32_e32 v111, v172
	v_pk_mul_f32 v[100:101], v[80:81], v[146:147] op_sel_hi:[1,0]
	v_pk_mul_f32 v[106:107], v[88:89], v[146:147] op_sel_hi:[1,0]
	v_pk_mul_f32 v[108:109], v[82:83], v[146:147] op_sel_hi:[1,0]
	v_pk_mul_f32 v[160:161], v[90:91], v[146:147] op_sel_hi:[1,0]
	v_pk_mul_f32 v[162:163], v[84:85], v[146:147] op_sel_hi:[1,0]
	v_pk_mul_f32 v[164:165], v[92:93], v[146:147] op_sel_hi:[1,0]
	v_mov_b32_e32 v167, v173
	s_waitcnt vmcnt(0)
	v_pk_mul_f32 v[174:175], v[106:107], v[96:97]
	s_waitcnt vmcnt(0)
	v_mul_f32_e32 v192, v166, v104
	v_pk_mul_f32 v[196:197], v[110:111], v[104:105]
	s_waitcnt vmcnt(0)
	v_mov_b32_e32 v104, v155
	v_pk_mul_f32 v[104:105], v[172:173], v[104:105]
	v_pk_mul_f32 v[96:97], v[100:101], v[96:97]
	v_pk_mul_f32 v[176:177], v[160:161], v[98:99]
	v_pk_mul_f32 v[98:99], v[108:109], v[98:99]
	v_pk_mul_f32 v[178:179], v[164:165], v[102:103]
	v_pk_mul_f32 v[102:103], v[162:163], v[102:103]
	v_mul_f32_e32 v194, v110, v154
	v_mov_b32_e32 v195, v104
	v_mov_b32_e32 v193, v105
	s_waitcnt vmcnt(0)
	v_pk_fma_f32 v[110:111], v[100:101], v[156:157], v[174:175] neg_lo:[0,0,1] neg_hi:[0,0,1]
	v_pk_fma_f32 v[100:101], v[106:107], v[156:157], v[96:97]
	v_pk_fma_f32 v[108:109], v[108:109], v[158:159], v[176:177] neg_lo:[0,0,1] neg_hi:[0,0,1]
	v_pk_fma_f32 v[98:99], v[160:161], v[158:159], v[98:99]
	v_pk_fma_f32 v[106:107], v[162:163], v[152:153], v[178:179] neg_lo:[0,0,1] neg_hi:[0,0,1]
	v_pk_fma_f32 v[96:97], v[164:165], v[152:153], v[102:103]
	v_pk_fma_f32 v[102:103], v[166:167], v[154:155], v[196:197] neg_lo:[0,0,1] neg_hi:[0,0,1]
	v_pk_add_f32 v[104:105], v[194:195], v[192:193]
; DI void phase2(const Params& p, unsigned char* smem, int tid) {
;     ...
;                 for (int it = 0; it < 4; ++it) {
;                     const int blk = (f * 256 + wi * 128 + it * 32) >> 5, hd = blk / 3, part = blk - hd * 3;
;                     if (part < 2) {
; #pragma unroll
;                         for (int r = 0; r < 16; ++r) acc[it][jt][r] *= rq;
;                     } else {
;                         const float* rp = rope + (size_t)pos * 32;
; #pragma unroll
;                         for (int g = 0; g < 2; ++g) {
;                             const f32x4 c4 = *(const f32x4*)(rp + 8 * g + 4 * h), s4 = *(const f32x4*)(rp + 16 + 8 * g + 4 * h);
; #pragma unroll
;                             for (int e = 0; e < 4; ++e) {
;                                 const float x1 = acc[it][jt][4 * g + e] * rq, x2 = acc[it][jt][4 * g + e + 8] * rq;
;                                 acc[it][jt][4 * g + e] = x1 * c4[e] - x2 * s4[e]; acc[it][jt][4 * g + e + 8] = x1 * s4[e] + x2 * c4[e];
;                             }
;                         }
;                     }
.LBB0_587:
	s_andn2_saveexec_b64 s[10:11], s[10:11]
	v_pk_mul_f32 v[104:105], v[94:95], v[146:147] op_sel_hi:[1,0]
	v_pk_mul_f32 v[96:97], v[92:93], v[146:147] op_sel_hi:[1,0]
	v_pk_mul_f32 v[98:99], v[90:91], v[146:147] op_sel_hi:[1,0]
	v_pk_mul_f32 v[100:101], v[88:89], v[146:147] op_sel_hi:[1,0]
	v_pk_mul_f32 v[102:103], v[86:87], v[146:147] op_sel_hi:[1,0]
	v_pk_mul_f32 v[106:107], v[84:85], v[146:147] op_sel_hi:[1,0]
	v_pk_mul_f32 v[108:109], v[82:83], v[146:147] op_sel_hi:[1,0]
	v_pk_mul_f32 v[110:111], v[80:81], v[146:147] op_sel_hi:[1,0]
	s_or_b64 exec, exec, s[10:11]
	v_or_b32_e32 v80, 3, v145
	v_mul_hi_i32 v81, v80, s87
	v_lshrrev_b32_e32 v82, 31, v81
	v_add_u32_e32 v81, v81, v82
	v_lshl_add_u32 v81, v81, 1, v81
	v_sub_u32_e32 v80, v80, v81
	v_cmp_lt_i32_e64 s[10:11], 1, v80
	s_and_saveexec_b64 s[12:13], s[10:11]
	s_xor_b64 s[12:13], exec, s[12:13]
	s_cbranch_execz .LBB0_591
	s_waitcnt vmcnt(0)
	v_mov_b64_e32 v[80:81], v[232:233]
	v_mov_b64_e32 v[82:83], v[234:235]
	s_waitcnt vmcnt(0)
	v_mov_b64_e32 v[86:87], v[240:241]
	v_mov_b64_e32 v[88:89], v[242:243]
	v_pk_mul_f32 v[90:91], v[64:65], v[146:147] op_sel_hi:[1,0]
	v_pk_mul_f32 v[92:93], v[72:73], v[146:147] op_sel_hi:[1,0]
	v_mov_b32_e32 v158, v79
	v_mov_b32_e32 v159, v71
	s_waitcnt vmcnt(0)
	v_pk_mul_f32 v[84:85], v[92:93], v[86:87]
	v_pk_mul_f32 v[86:87], v[90:91], v[86:87]
	v_pk_fma_f32 v[84:85], v[90:91], v[80:81], v[84:85] neg_lo:[0,0,1] neg_hi:[0,0,1]
	v_pk_fma_f32 v[80:81], v[92:93], v[80:81], v[86:87]
	v_pk_mul_f32 v[90:91], v[66:67], v[146:147] op_sel_hi:[1,0]
	v_pk_mul_f32 v[92:93], v[74:75], v[146:147] op_sel_hi:[1,0]
	s_nop 0
	v_pk_mul_f32 v[86:87], v[92:93], v[88:89]
	v_pk_mul_f32 v[88:89], v[90:91], v[88:89]
	v_pk_fma_f32 v[86:87], v[90:91], v[82:83], v[86:87] neg_lo:[0,0,1] neg_hi:[0,0,1]
	v_pk_fma_f32 v[82:83], v[92:93], v[82:83], v[88:89]
	s_waitcnt vmcnt(0)
	v_mov_b64_e32 v[92:93], v[236:237]
	v_mov_b64_e32 v[94:95], v[238:239]
	s_waitcnt vmcnt(0)
	v_mov_b64_e32 v[152:153], v[248:249]
	v_mov_b64_e32 v[154:155], v[250:251]
	v_pk_mul_f32 v[148:149], v[76:77], v[146:147] op_sel_hi:[1,0]
	v_pk_mul_f32 v[88:89], v[68:69], v[146:147] op_sel_hi:[1,0]
	s_waitcnt vmcnt(0)
	v_pk_mul_f32 v[90:91], v[148:149], v[152:153]
	s_nop 0
	v_pk_fma_f32 v[90:91], v[88:89], v[92:93], v[90:91] neg_lo:[0,0,1] neg_hi:[0,0,1]
	v_pk_mul_f32 v[88:89], v[88:89], v[152:153]
	s_nop 0
	v_pk_fma_f32 v[88:89], v[148:149], v[92:93], v[88:89]
	v_mul_f32_e32 v92, v70, v146
	v_mul_f32_e32 v148, v78, v146
	v_pk_mul_f32 v[146:147], v[158:159], v[146:147] op_sel_hi:[1,0]
	v_mul_f32_e32 v152, v92, v154
	v_mov_b32_e32 v149, v146
	v_mul_f32_e32 v156, v148, v94
	v_mov_b32_e32 v93, v147
	v_pk_mul_f32 v[148:149], v[148:149], v[154:155]
	v_mov_b32_e32 v154, v95
	v_pk_fma_f32 v[92:93], v[92:93], v[94:95], v[148:149] neg_lo:[0,0,1] neg_hi:[0,0,1]
	v_pk_mul_f32 v[94:95], v[146:147], v[154:155]
	s_nop 0
	v_mov_b32_e32 v157, v94
	v_mov_b32_e32 v153, v95
	v_pk_add_f32 v[94:95], v[156:157], v[152:153]
; DI void phase2(const Params& p, unsigned char* smem, int tid) {
;     ...
;             for (int jt = 0; jt < 2; ++jt) {
;                 const int tl = wj * 64 + jt * 32 + ln, t = tt * 256 + tl;
;                 const float rq = MLA_QS / sqrtf(((const float*)(ws + OFF_SSQC))[t] * (1.0f / 256) + EPS);
;                 const int pos = t % L;
; #pragma unroll
;                 for (int it = 0; it < 4; ++it) {
;                     const int blk = (f * 256 + wi * 128 + it * 32) >> 5, hd = blk / 3, part = blk - hd * 3;
;                     if (part < 2) {
; #pragma unroll
;                         for (int r = 0; r < 16; ++r) acc[it][jt][r] *= rq;
;                     } else {
;                         const float* rp = rope + (size_t)pos * 32;
; #pragma unroll
;                         for (int g = 0; g < 2; ++g) {
;                             const f32x4 c4 = *(const f32x4*)(rp + 8 * g + 4 * h), s4 = *(const f32x4*)(rp + 16 + 8 * g + 4 * h);
; #pragma unroll
;                             for (int e = 0; e < 4; ++e) {
;                                 const float x1 = acc[it][jt][4 * g + e] * rq, x2 = acc[it][jt][4 * g + e + 8] * rq;
;                                 acc[it][jt][4 * g + e] = x1 * c4[e] - x2 * s4[e]; acc[it][jt][4 * g + e + 8] = x1 * s4[e] + x2 * c4[e];
;                             }
;                         }
;                     }
.LBB0_591:
	s_andn2_saveexec_b64 s[12:13], s[12:13]
	v_pk_mul_f32 v[94:95], v[78:79], v[146:147] op_sel_hi:[1,0]
	v_pk_mul_f32 v[88:89], v[76:77], v[146:147] op_sel_hi:[1,0]
	v_pk_mul_f32 v[82:83], v[74:75], v[146:147] op_sel_hi:[1,0]
	v_pk_mul_f32 v[80:81], v[72:73], v[146:147] op_sel_hi:[1,0]
	v_pk_mul_f32 v[92:93], v[70:71], v[146:147] op_sel_hi:[1,0]
	v_pk_mul_f32 v[90:91], v[68:69], v[146:147] op_sel_hi:[1,0]
	v_pk_mul_f32 v[86:87], v[66:67], v[146:147] op_sel_hi:[1,0]
	v_pk_mul_f32 v[84:85], v[64:65], v[146:147] op_sel_hi:[1,0]
	s_or_b64 exec, exec, s[12:13]
	v_or_b32_e32 v64, 32, v144
	v_ashrrev_i32_e32 v65, 31, v64
	v_lshl_add_u64 v[66:67], v[64:65], 2, s[34:35]
	v_mov_b32_e32 v65, v254
	v_mul_hi_i32 v66, v64, s62
	v_lshrrev_b32_e32 v67, 31, v66
	v_ashrrev_i32_e32 v66, 11, v66
	v_add_u32_e32 v66, v66, v67
	v_mul_i32_i24_e32 v66, 0x1010, v66
	v_sub_u32_e32 v64, v64, v66
	v_ashrrev_i32_e32 v253, 31, v64
	v_mov_b32_e32 v252, v64
	v_lshlrev_b64 v[252:253], 7, v[252:253]
	v_lshl_add_u64 v[252:253], s[18:19], 0, v[252:253]
	v_lshl_add_u64 v[252:253], v[252:253], 0, v[168:169]
	global_load_dwordx4 v[232:235], v[252:253], off
	global_load_dwordx4 v[236:239], v[252:253], off offset:32
	global_load_dwordx4 v[240:243], v[252:253], off offset:64
	global_load_dwordx4 v[248:251], v[252:253], off offset:96
	v_fmamk_f32 v65, v65, 0x3b800000, v181
	v_mul_f32_e32 v67, 0x4f800000, v65
	v_cmp_gt_f32_e32 vcc, s85, v65
	s_nop 1
	v_cndmask_b32_e32 v67, v65, v67, vcc
	v_sqrt_f32_e32 v68, v67
	v_ashrrev_i32_e32 v65, 31, v64
	v_lshlrev_b64 v[64:65], 7, v[64:65]
	v_lshl_add_u64 v[64:65], s[18:19], 0, v[64:65]
	v_add_u32_e32 v66, -1, v68
	v_add_u32_e32 v69, 1, v68
	v_fma_f32 v70, -v66, v68, v67
	v_fma_f32 v71, -v69, v68, v67
	v_cmp_ge_f32_e64 s[12:13], 0, v70
	v_lshl_add_u64 v[146:147], v[64:65], 0, v[168:169]
	s_nop 0
	v_cndmask_b32_e64 v66, v68, v66, s[12:13]
	v_cmp_lt_f32_e64 s[12:13], 0, v71
	s_nop 1
	v_cndmask_b32_e64 v66, v66, v69, s[12:13]
	v_mul_f32_e32 v68, 0x37800000, v66
	v_cndmask_b32_e32 v66, v66, v68, vcc
	v_cmp_class_f32_e32 vcc, v67, v182
	s_nop 1
	v_cndmask_b32_e32 v66, v66, v67, vcc
	v_div_scale_f32 v67, s[12:13], v66, v66, s86
	v_rcp_f32_e32 v68, v67
	v_div_scale_f32 v69, vcc, s86, v66, s86
	v_fma_f32 v70, -v67, v68, 1.0
	v_fmac_f32_e32 v68, v70, v68
	v_mul_f32_e32 v70, v69, v68
	v_fma_f32 v71, -v67, v70, v69
	v_fmac_f32_e32 v70, v71, v68
	v_fma_f32 v67, -v67, v70, v69
	v_div_fmas_f32 v67, v67, v68, v70
	v_div_fixup_f32 v144, v67, v66, s86
	s_and_saveexec_b64 s[12:13], s[4:5]
	s_xor_b64 s[4:5], exec, s[12:13]
	s_cbranch_execz .LBB0_595
	s_waitcnt vmcnt(0)
	v_mov_b64_e32 v[64:65], v[240:241]
	v_mov_b64_e32 v[66:67], v[242:243]
	s_waitcnt vmcnt(0)
	v_mov_b64_e32 v[70:71], v[248:249]
	v_mov_b64_e32 v[72:73], v[250:251]
	s_waitcnt vmcnt(0)
	v_mov_b64_e32 v[152:153], v[236:237]
	v_mov_b64_e32 v[154:155], v[238:239]
	s_waitcnt vmcnt(0)
	v_mov_b64_e32 v[156:157], v[232:233]
	v_mov_b64_e32 v[158:159], v[234:235]
	v_mov_b32_e32 v166, v63
	v_mov_b32_e32 v167, v55
	v_pk_mul_f32 v[166:167], v[166:167], v[144:145] op_sel_hi:[1,0]
	v_mul_f32_e32 v164, v54, v144
	v_mul_f32_e32 v78, v62, v144
	v_mov_b32_e32 v79, v166
	v_pk_mul_f32 v[68:69], v[48:49], v[144:145] op_sel_hi:[1,0]
	v_pk_mul_f32 v[74:75], v[56:57], v[144:145] op_sel_hi:[1,0]
	v_pk_mul_f32 v[76:77], v[50:51], v[144:145] op_sel_hi:[1,0]
	v_pk_mul_f32 v[148:149], v[58:59], v[144:145] op_sel_hi:[1,0]
	v_pk_mul_f32 v[160:161], v[52:53], v[144:145] op_sel_hi:[1,0]
	v_pk_mul_f32 v[162:163], v[60:61], v[144:145] op_sel_hi:[1,0]
	v_mov_b32_e32 v165, v167
	s_waitcnt vmcnt(0)
	v_pk_mul_f32 v[172:173], v[74:75], v[64:65]
	s_waitcnt vmcnt(0)
	v_mul_f32_e32 v178, v164, v72
	v_pk_mul_f32 v[194:195], v[78:79], v[72:73]
	s_waitcnt vmcnt(0)
	v_mov_b32_e32 v72, v155
	v_pk_mul_f32 v[72:73], v[166:167], v[72:73]
	v_pk_mul_f32 v[64:65], v[68:69], v[64:65]
	v_pk_mul_f32 v[174:175], v[148:149], v[66:67]
	v_pk_mul_f32 v[66:67], v[76:77], v[66:67]
	v_pk_mul_f32 v[176:177], v[162:163], v[70:71]
	v_pk_mul_f32 v[70:71], v[160:161], v[70:71]
	v_mul_f32_e32 v192, v78, v154
	v_mov_b32_e32 v193, v72
	v_mov_b32_e32 v179, v73
	s_waitcnt vmcnt(0)
	v_pk_fma_f32 v[78:79], v[68:69], v[156:157], v[172:173] neg_lo:[0,0,1] neg_hi:[0,0,1]
	v_pk_fma_f32 v[68:69], v[74:75], v[156:157], v[64:65]
	v_pk_fma_f32 v[76:77], v[76:77], v[158:159], v[174:175] neg_lo:[0,0,1] neg_hi:[0,0,1]
	v_pk_fma_f32 v[66:67], v[148:149], v[158:159], v[66:67]
	v_pk_fma_f32 v[74:75], v[160:161], v[152:153], v[176:177] neg_lo:[0,0,1] neg_hi:[0,0,1]
	v_pk_fma_f32 v[64:65], v[162:163], v[152:153], v[70:71]
	v_pk_fma_f32 v[70:71], v[164:165], v[154:155], v[194:195] neg_lo:[0,0,1] neg_hi:[0,0,1]
	v_pk_add_f32 v[72:73], v[192:193], v[178:179]
	s_andn2_saveexec_b64 s[4:5], s[4:5]
	s_branch .LBB0_596

; DI void phase2(const Params& p, unsigned char* smem, int tid) {
;     ...
;                 for (int it = 0; it < 4; ++it) {
;                     const int blk = (f * 256 + wi * 128 + it * 32) >> 5, hd = blk / 3, part = blk - hd * 3;
;                     if (part < 2) {
; #pragma unroll
;                         for (int r = 0; r < 16; ++r) acc[it][jt][r] *= rq;
;                     } else {
;                         const float* rp = rope + (size_t)pos * 32;
; #pragma unroll
;                         for (int g = 0; g < 2; ++g) {
;                             const f32x4 c4 = *(const f32x4*)(rp + 8 * g + 4 * h), s4 = *(const f32x4*)(rp + 16 + 8 * g + 4 * h);
; #pragma unroll
;                             for (int e = 0; e < 4; ++e) {
;                                 const float x1 = acc[it][jt][4 * g + e] * rq, x2 = acc[it][jt][4 * g + e + 8] * rq;
;                                 acc[it][jt][4 * g + e] = x1 * c4[e] - x2 * s4[e]; acc[it][jt][4 * g + e + 8] = x1 * s4[e] + x2 * c4[e];
;                             }
;                         }
;                     }
.LBB0_596:
	v_pk_mul_f32 v[72:73], v[62:63], v[144:145] op_sel_hi:[1,0]
	v_pk_mul_f32 v[64:65], v[60:61], v[144:145] op_sel_hi:[1,0]
	v_pk_mul_f32 v[66:67], v[58:59], v[144:145] op_sel_hi:[1,0]
	v_pk_mul_f32 v[68:69], v[56:57], v[144:145] op_sel_hi:[1,0]
	v_pk_mul_f32 v[70:71], v[54:55], v[144:145] op_sel_hi:[1,0]
	v_pk_mul_f32 v[74:75], v[52:53], v[144:145] op_sel_hi:[1,0]
	v_pk_mul_f32 v[76:77], v[50:51], v[144:145] op_sel_hi:[1,0]
	v_pk_mul_f32 v[78:79], v[48:49], v[144:145] op_sel_hi:[1,0]
	s_or_b64 exec, exec, s[4:5]
	s_and_saveexec_b64 s[4:5], s[6:7]
	s_xor_b64 s[4:5], exec, s[4:5]
	s_cbranch_execz .LBB0_599
	s_waitcnt vmcnt(0)
	v_mov_b64_e32 v[48:49], v[240:241]
	v_mov_b64_e32 v[50:51], v[242:243]
	s_waitcnt vmcnt(0)
	v_mov_b64_e32 v[54:55], v[248:249]
	v_mov_b64_e32 v[56:57], v[250:251]
	s_waitcnt vmcnt(0)
	v_mov_b64_e32 v[152:153], v[236:237]
	v_mov_b64_e32 v[154:155], v[238:239]
	s_waitcnt vmcnt(0)
	v_mov_b64_e32 v[156:157], v[232:233]
	v_mov_b64_e32 v[158:159], v[234:235]
	v_mov_b32_e32 v166, v47
	v_mov_b32_e32 v167, v39
	v_pk_mul_f32 v[166:167], v[166:167], v[144:145] op_sel_hi:[1,0]
	v_mul_f32_e32 v164, v38, v144
	v_mul_f32_e32 v62, v46, v144
	v_mov_b32_e32 v63, v166
	v_pk_mul_f32 v[52:53], v[32:33], v[144:145] op_sel_hi:[1,0]
	v_pk_mul_f32 v[58:59], v[40:41], v[144:145] op_sel_hi:[1,0]
	v_pk_mul_f32 v[60:61], v[34:35], v[144:145] op_sel_hi:[1,0]
	v_pk_mul_f32 v[148:149], v[42:43], v[144:145] op_sel_hi:[1,0]
	v_pk_mul_f32 v[160:161], v[36:37], v[144:145] op_sel_hi:[1,0]
	v_pk_mul_f32 v[162:163], v[44:45], v[144:145] op_sel_hi:[1,0]
	v_mov_b32_e32 v165, v167
	s_waitcnt vmcnt(0)
	v_pk_mul_f32 v[172:173], v[58:59], v[48:49]
	s_waitcnt vmcnt(0)
	v_mul_f32_e32 v178, v164, v56
	v_pk_mul_f32 v[194:195], v[62:63], v[56:57]
	s_waitcnt vmcnt(0)
	v_mov_b32_e32 v56, v155
	v_pk_mul_f32 v[56:57], v[166:167], v[56:57]
	v_pk_mul_f32 v[48:49], v[52:53], v[48:49]
	v_pk_mul_f32 v[174:175], v[148:149], v[50:51]
	v_pk_mul_f32 v[50:51], v[60:61], v[50:51]
	v_pk_mul_f32 v[176:177], v[162:163], v[54:55]
	v_pk_mul_f32 v[54:55], v[160:161], v[54:55]
	v_mul_f32_e32 v192, v62, v154
	v_mov_b32_e32 v193, v56
	v_mov_b32_e32 v179, v57
	s_waitcnt vmcnt(0)
	v_pk_fma_f32 v[62:63], v[52:53], v[156:157], v[172:173] neg_lo:[0,0,1] neg_hi:[0,0,1]
	v_pk_fma_f32 v[52:53], v[58:59], v[156:157], v[48:49]
	v_pk_fma_f32 v[60:61], v[60:61], v[158:159], v[174:175] neg_lo:[0,0,1] neg_hi:[0,0,1]
	v_pk_fma_f32 v[50:51], v[148:149], v[158:159], v[50:51]
	v_pk_fma_f32 v[58:59], v[160:161], v[152:153], v[176:177] neg_lo:[0,0,1] neg_hi:[0,0,1]
	v_pk_fma_f32 v[48:49], v[162:163], v[152:153], v[54:55]
	v_pk_fma_f32 v[54:55], v[164:165], v[154:155], v[194:195] neg_lo:[0,0,1] neg_hi:[0,0,1]
	v_pk_add_f32 v[56:57], v[192:193], v[178:179]
	s_andn2_saveexec_b64 s[4:5], s[4:5]
	s_branch .LBB0_600

; DI void phase2(const Params& p, unsigned char* smem, int tid) {
;     ...
;                 for (int it = 0; it < 4; ++it) {
;                     const int blk = (f * 256 + wi * 128 + it * 32) >> 5, hd = blk / 3, part = blk - hd * 3;
;                     if (part < 2) {
; #pragma unroll
;                         for (int r = 0; r < 16; ++r) acc[it][jt][r] *= rq;
;                     } else {
;                         const float* rp = rope + (size_t)pos * 32;
; #pragma unroll
;                         for (int g = 0; g < 2; ++g) {
;                             const f32x4 c4 = *(const f32x4*)(rp + 8 * g + 4 * h), s4 = *(const f32x4*)(rp + 16 + 8 * g + 4 * h);
; #pragma unroll
;                             for (int e = 0; e < 4; ++e) {
;                                 const float x1 = acc[it][jt][4 * g + e] * rq, x2 = acc[it][jt][4 * g + e + 8] * rq;
;                                 acc[it][jt][4 * g + e] = x1 * c4[e] - x2 * s4[e]; acc[it][jt][4 * g + e + 8] = x1 * s4[e] + x2 * c4[e];
;                             }
;                         }
;                     }
.LBB0_600:
	v_pk_mul_f32 v[56:57], v[46:47], v[144:145] op_sel_hi:[1,0]
	v_pk_mul_f32 v[48:49], v[44:45], v[144:145] op_sel_hi:[1,0]
	v_pk_mul_f32 v[50:51], v[42:43], v[144:145] op_sel_hi:[1,0]
	v_pk_mul_f32 v[52:53], v[40:41], v[144:145] op_sel_hi:[1,0]
	v_pk_mul_f32 v[54:55], v[38:39], v[144:145] op_sel_hi:[1,0]
	v_pk_mul_f32 v[58:59], v[36:37], v[144:145] op_sel_hi:[1,0]
	v_pk_mul_f32 v[60:61], v[34:35], v[144:145] op_sel_hi:[1,0]
	v_pk_mul_f32 v[62:63], v[32:33], v[144:145] op_sel_hi:[1,0]
	s_or_b64 exec, exec, s[4:5]
	s_and_saveexec_b64 s[4:5], s[8:9]
	s_xor_b64 s[4:5], exec, s[4:5]
	s_cbranch_execz .LBB0_603
	s_waitcnt vmcnt(0)
	v_mov_b64_e32 v[32:33], v[240:241]
	v_mov_b64_e32 v[34:35], v[242:243]
	s_waitcnt vmcnt(0)
	v_mov_b64_e32 v[38:39], v[248:249]
	v_mov_b64_e32 v[40:41], v[250:251]
	s_waitcnt vmcnt(0)
	v_mov_b64_e32 v[152:153], v[236:237]
	v_mov_b64_e32 v[154:155], v[238:239]
	s_waitcnt vmcnt(0)
	v_mov_b64_e32 v[156:157], v[232:233]
	v_mov_b64_e32 v[158:159], v[234:235]
	v_mov_b32_e32 v166, v31
	v_mov_b32_e32 v167, v23
	v_pk_mul_f32 v[166:167], v[166:167], v[144:145] op_sel_hi:[1,0]
	v_mul_f32_e32 v164, v22, v144
	v_mul_f32_e32 v46, v30, v144
	v_mov_b32_e32 v47, v166
	v_pk_mul_f32 v[36:37], v[16:17], v[144:145] op_sel_hi:[1,0]
	v_pk_mul_f32 v[42:43], v[24:25], v[144:145] op_sel_hi:[1,0]
	v_pk_mul_f32 v[44:45], v[18:19], v[144:145] op_sel_hi:[1,0]
	v_pk_mul_f32 v[148:149], v[26:27], v[144:145] op_sel_hi:[1,0]
	v_pk_mul_f32 v[160:161], v[20:21], v[144:145] op_sel_hi:[1,0]
	v_pk_mul_f32 v[162:163], v[28:29], v[144:145] op_sel_hi:[1,0]
	v_mov_b32_e32 v165, v167
	s_waitcnt vmcnt(0)
	v_pk_mul_f32 v[172:173], v[42:43], v[32:33]
	s_waitcnt vmcnt(0)
	v_mul_f32_e32 v178, v164, v40
	v_pk_mul_f32 v[194:195], v[46:47], v[40:41]
	s_waitcnt vmcnt(0)
	v_mov_b32_e32 v40, v155
	v_pk_mul_f32 v[40:41], v[166:167], v[40:41]
	v_pk_mul_f32 v[32:33], v[36:37], v[32:33]
	v_pk_mul_f32 v[174:175], v[148:149], v[34:35]
	v_pk_mul_f32 v[34:35], v[44:45], v[34:35]
	v_pk_mul_f32 v[176:177], v[162:163], v[38:39]
	v_pk_mul_f32 v[38:39], v[160:161], v[38:39]
	v_mul_f32_e32 v192, v46, v154
	v_mov_b32_e32 v193, v40
	v_mov_b32_e32 v179, v41
	s_waitcnt vmcnt(0)
	v_pk_fma_f32 v[46:47], v[36:37], v[156:157], v[172:173] neg_lo:[0,0,1] neg_hi:[0,0,1]
	v_pk_fma_f32 v[36:37], v[42:43], v[156:157], v[32:33]
	v_pk_fma_f32 v[44:45], v[44:45], v[158:159], v[174:175] neg_lo:[0,0,1] neg_hi:[0,0,1]
	v_pk_fma_f32 v[34:35], v[148:149], v[158:159], v[34:35]
	v_pk_fma_f32 v[42:43], v[160:161], v[152:153], v[176:177] neg_lo:[0,0,1] neg_hi:[0,0,1]
	v_pk_fma_f32 v[32:33], v[162:163], v[152:153], v[38:39]
	v_pk_fma_f32 v[38:39], v[164:165], v[154:155], v[194:195] neg_lo:[0,0,1] neg_hi:[0,0,1]
	v_pk_add_f32 v[40:41], v[192:193], v[178:179]
	s_andn2_saveexec_b64 s[4:5], s[4:5]
	s_branch .LBB0_604

; DI void phase2(const Params& p, unsigned char* smem, int tid) {
;     ...
;                 for (int it = 0; it < 4; ++it) {
;                     const int blk = (f * 256 + wi * 128 + it * 32) >> 5, hd = blk / 3, part = blk - hd * 3;
;                     if (part < 2) {
; #pragma unroll
;                         for (int r = 0; r < 16; ++r) acc[it][jt][r] *= rq;
;                     } else {
;                         const float* rp = rope + (size_t)pos * 32;
; #pragma unroll
;                         for (int g = 0; g < 2; ++g) {
;                             const f32x4 c4 = *(const f32x4*)(rp + 8 * g + 4 * h), s4 = *(const f32x4*)(rp + 16 + 8 * g + 4 * h);
; #pragma unroll
;                             for (int e = 0; e < 4; ++e) {
;                                 const float x1 = acc[it][jt][4 * g + e] * rq, x2 = acc[it][jt][4 * g + e + 8] * rq;
;                                 acc[it][jt][4 * g + e] = x1 * c4[e] - x2 * s4[e]; acc[it][jt][4 * g + e + 8] = x1 * s4[e] + x2 * c4[e];
;                             }
;                         }
;                     }
.LBB0_604:
	v_pk_mul_f32 v[40:41], v[30:31], v[144:145] op_sel_hi:[1,0]
	v_pk_mul_f32 v[32:33], v[28:29], v[144:145] op_sel_hi:[1,0]
	v_pk_mul_f32 v[34:35], v[26:27], v[144:145] op_sel_hi:[1,0]
	v_pk_mul_f32 v[36:37], v[24:25], v[144:145] op_sel_hi:[1,0]
	v_pk_mul_f32 v[38:39], v[22:23], v[144:145] op_sel_hi:[1,0]
	v_pk_mul_f32 v[42:43], v[20:21], v[144:145] op_sel_hi:[1,0]
	v_pk_mul_f32 v[44:45], v[18:19], v[144:145] op_sel_hi:[1,0]
	v_pk_mul_f32 v[46:47], v[16:17], v[144:145] op_sel_hi:[1,0]
	s_or_b64 exec, exec, s[4:5]
	s_and_saveexec_b64 s[4:5], s[10:11]
	s_xor_b64 s[4:5], exec, s[4:5]
	s_cbranch_execz .LBB0_607
	s_waitcnt vmcnt(0)
	v_mov_b64_e32 v[16:17], v[240:241]
	v_mov_b64_e32 v[18:19], v[242:243]
	s_waitcnt vmcnt(0)
	v_mov_b64_e32 v[22:23], v[248:249]
	v_mov_b64_e32 v[24:25], v[250:251]
	s_waitcnt vmcnt(0)
	v_mov_b64_e32 v[152:153], v[236:237]
	v_mov_b64_e32 v[154:155], v[238:239]
	s_nop 0
	s_waitcnt vmcnt(0)
	v_mov_b64_e32 v[146:147], v[232:233]
	v_mov_b64_e32 v[148:149], v[234:235]
	v_mov_b32_e32 v164, v15
	v_mov_b32_e32 v165, v7
	v_pk_mul_f32 v[20:21], v[0:1], v[144:145] op_sel_hi:[1,0]
	v_pk_mul_f32 v[26:27], v[8:9], v[144:145] op_sel_hi:[1,0]
	v_pk_mul_f32 v[28:29], v[2:3], v[144:145] op_sel_hi:[1,0]
	v_pk_mul_f32 v[156:157], v[10:11], v[144:145] op_sel_hi:[1,0]
	v_pk_mul_f32 v[158:159], v[4:5], v[144:145] op_sel_hi:[1,0]
	v_pk_mul_f32 v[160:161], v[12:13], v[144:145] op_sel_hi:[1,0]
	v_mul_f32_e32 v162, v6, v144
	v_mul_f32_e32 v30, v14, v144
	v_pk_mul_f32 v[144:145], v[164:165], v[144:145] op_sel_hi:[1,0]
	s_waitcnt vmcnt(0)
	v_pk_mul_f32 v[164:165], v[26:27], v[16:17]
	v_mov_b32_e32 v31, v144
	s_waitcnt vmcnt(0)
	v_mul_f32_e32 v174, v162, v24
	v_pk_mul_f32 v[178:179], v[30:31], v[24:25]
	s_waitcnt vmcnt(0)
	v_mov_b32_e32 v24, v155
	v_pk_mul_f32 v[24:25], v[144:145], v[24:25]
	v_mov_b32_e32 v163, v145
	v_pk_mul_f32 v[16:17], v[20:21], v[16:17]
	v_pk_mul_f32 v[166:167], v[156:157], v[18:19]
	v_pk_mul_f32 v[18:19], v[28:29], v[18:19]
	v_pk_mul_f32 v[172:173], v[160:161], v[22:23]
	v_pk_mul_f32 v[22:23], v[158:159], v[22:23]
	v_mul_f32_e32 v176, v30, v154
	v_mov_b32_e32 v177, v24
	v_mov_b32_e32 v175, v25
	s_waitcnt vmcnt(0)
	v_pk_fma_f32 v[30:31], v[20:21], v[146:147], v[164:165] neg_lo:[0,0,1] neg_hi:[0,0,1]
	v_pk_fma_f32 v[20:21], v[26:27], v[146:147], v[16:17]
	v_pk_fma_f32 v[28:29], v[28:29], v[148:149], v[166:167] neg_lo:[0,0,1] neg_hi:[0,0,1]
	v_pk_fma_f32 v[18:19], v[156:157], v[148:149], v[18:19]
	v_pk_fma_f32 v[26:27], v[158:159], v[152:153], v[172:173] neg_lo:[0,0,1] neg_hi:[0,0,1]
	v_pk_fma_f32 v[16:17], v[160:161], v[152:153], v[22:23]
	v_pk_fma_f32 v[22:23], v[162:163], v[154:155], v[178:179] neg_lo:[0,0,1] neg_hi:[0,0,1]
	v_pk_add_f32 v[24:25], v[176:177], v[174:175]
	s_andn2_saveexec_b64 s[4:5], s[4:5]
	s_cbranch_execnz .LBB0_608
	s_branch .LBB0_609
